# code placement A/B: the whole attention tile loop shifted by 4 bytes (one s_nop in front of the loop head), otherwise identical to the best version
# speedup vs baseline: 1.0059x; 1.0059x over previous
; #define LAS __attribute__((address_space(3)))
; #define DIFF_ISSUE(T_) do { const unsigned sb_ = lbase + (unsigned)((T_) & 3) * 32768u; const bf16* k_ = gk + (size_t)(T_) * (64 * 512); const bf16* v_ = gv + (size_t)(T_) * 64; \
;         glds16(k_, sb_); glds16(k_ + 64, sb_ + 8192u); glds16(v_, sb_ + 16384u); glds16(v_ + (size_t)64 * VPITCH, sb_ + 24576u); } while (0)
; __device__ __forceinline__ void diff_unit_lds(LAS unsigned char* lds, const bf16* Qd, const bf16* Kd, const bf16* VdT, bf16* MIX, const float* ghead, float lam, int head, int u, int wave, int lane) {
;     ...
; #pragma unroll 2
;     for (int T = 0; T < nT; ++T) {
;         LAS unsigned char* st = lds + (T & 3) * 32768;
;         if ((T & 1) == 0) {
;             asm volatile("s_waitcnt vmcnt(0) lgkmcnt(0)\n\ts_barrier" ::: "memory");
;             if (T + 2 < nT) DIFF_ISSUE(T + 2);
;             if (T + 3 < nT) DIFF_ISSUE(T + 3);
;         }
.Lq_prio_done:
	s_nop 0
